# MoBA gating-score loop: 16 key-mean LDS reads issued together; plus diagonal-item bias lookups pipelined and early L2 writeback by first barrier arriver
# speedup vs baseline: 1.0039x; 1.0039x over previous
; __device__ __forceinline__ void moba_unit(const Ctx& C, int unit, const float* KM) {
;     ...
;         for (int n = half; n < qb; n += 2) {
;             float s = 0.f;
; #pragma unroll
;             for (int e = 0; e < 64; ++e) s += qf[e] * kml[n * 64 + e];
;             if (s > v1) { v3 = v2; i3 = i2; v2 = v1; i2 = i1; v1 = s; i1 = n; }
;             else if (s > v2) { v3 = v2; i3 = i2; v2 = s; i2 = n; }
;             else if (s > v3) { v3 = s; i3 = n; }
;         }
.LBB0_419:
	v_lshl_add_u32 v36, v75, 8, 0
	v_add_u32_e32 v36, 0x16000, v36
	ds_read_b128 v[80:83], v36
	ds_read_b128 v[84:87], v36 offset:16
	ds_read_b128 v[88:91], v36 offset:32
	ds_read_b128 v[92:95], v36 offset:48
	ds_read_b128 v[96:99], v36 offset:64
	ds_read_b128 v[100:103], v36 offset:80
	ds_read_b128 v[104:107], v36 offset:96
	ds_read_b128 v[108:111], v36 offset:112
	ds_read_b128 v[112:115], v36 offset:128
	ds_read_b128 v[116:119], v36 offset:144
	ds_read_b128 v[120:123], v36 offset:160
	ds_read_b128 v[124:127], v36 offset:176
	ds_read_b128 v[128:131], v36 offset:192
	ds_read_b128 v[134:137], v36 offset:208
	ds_read_b128 v[138:141], v36 offset:224
	ds_read_b128 v[142:145], v36 offset:240
	s_waitcnt lgkmcnt(15)
	v_fma_f32 v39, v80, v43, 0
	v_fmac_f32_e32 v39, v81, v28
	v_fmac_f32_e32 v39, v82, v44
	v_fmac_f32_e32 v39, v83, v29
	s_waitcnt lgkmcnt(14)
	v_fmac_f32_e32 v39, v84, v45
	v_fmac_f32_e32 v39, v85, v30
	v_fmac_f32_e32 v39, v86, v46
	v_fmac_f32_e32 v39, v87, v31
	s_waitcnt lgkmcnt(13)
	v_fmac_f32_e32 v39, v88, v47
	v_fmac_f32_e32 v39, v89, v24
	v_fmac_f32_e32 v39, v90, v48
	v_fmac_f32_e32 v39, v91, v25
	s_waitcnt lgkmcnt(12)
	v_fmac_f32_e32 v39, v92, v49
	v_fmac_f32_e32 v39, v93, v26
	v_fmac_f32_e32 v39, v94, v50
	v_fmac_f32_e32 v39, v95, v27
	s_waitcnt lgkmcnt(11)
	v_fmac_f32_e32 v39, v96, v51
	v_fmac_f32_e32 v39, v97, v20
	v_fmac_f32_e32 v39, v98, v52
	v_fmac_f32_e32 v39, v99, v21
	s_waitcnt lgkmcnt(10)
	v_fmac_f32_e32 v39, v100, v53
	v_fmac_f32_e32 v39, v101, v22
	v_fmac_f32_e32 v39, v102, v54
	v_fmac_f32_e32 v39, v103, v23
	s_waitcnt lgkmcnt(9)
	v_fmac_f32_e32 v39, v104, v55
	v_fmac_f32_e32 v39, v105, v16
	v_fmac_f32_e32 v39, v106, v56
	v_fmac_f32_e32 v39, v107, v17
	s_waitcnt lgkmcnt(8)
	v_fmac_f32_e32 v39, v108, v57
	v_fmac_f32_e32 v39, v109, v18
	v_fmac_f32_e32 v39, v110, v58
	v_fmac_f32_e32 v39, v111, v19
	s_waitcnt lgkmcnt(7)
	v_fmac_f32_e32 v39, v112, v59
	v_fmac_f32_e32 v39, v113, v12
	v_fmac_f32_e32 v39, v114, v60
	v_fmac_f32_e32 v39, v115, v13
	s_waitcnt lgkmcnt(6)
	v_fmac_f32_e32 v39, v116, v61
	v_fmac_f32_e32 v39, v117, v14
	v_fmac_f32_e32 v39, v118, v62
	v_fmac_f32_e32 v39, v119, v15
	s_waitcnt lgkmcnt(5)
	v_fmac_f32_e32 v39, v120, v63
	v_fmac_f32_e32 v39, v121, v64
	v_fmac_f32_e32 v39, v122, v65
	v_fmac_f32_e32 v39, v123, v66
	s_waitcnt lgkmcnt(4)
	v_fmac_f32_e32 v39, v124, v67
	v_fmac_f32_e32 v39, v125, v68
	v_fmac_f32_e32 v39, v126, v69
	v_fmac_f32_e32 v39, v127, v70
	s_waitcnt lgkmcnt(3)
	v_fmac_f32_e32 v39, v128, v71
	v_fmac_f32_e32 v39, v129, v72
	v_fmac_f32_e32 v39, v130, v73
	v_fmac_f32_e32 v39, v131, v74
	s_waitcnt lgkmcnt(2)
	v_pk_mul_f32 v[40:41], v[134:135], v[4:5]
	s_nop 0
	v_add_f32_e32 v39, v39, v40
	v_add_f32_e32 v39, v39, v41
	v_pk_mul_f32 v[40:41], v[136:137], v[6:7]
	v_add_f32_e32 v39, v39, v40
	v_add_f32_e32 v39, v39, v41
	s_waitcnt lgkmcnt(1)
	v_pk_mul_f32 v[40:41], v[138:139], v[8:9]
	s_nop 0
	v_add_f32_e32 v39, v39, v40
	v_add_f32_e32 v39, v39, v41
	v_pk_mul_f32 v[40:41], v[140:141], v[0:1]
	v_add_f32_e32 v39, v39, v40
	v_add_f32_e32 v39, v39, v41
	s_waitcnt lgkmcnt(0)
	v_pk_mul_f32 v[40:41], v[142:143], v[10:11]
	s_nop 0
	v_add_f32_e32 v36, v39, v40
	v_add_f32_e32 v36, v36, v41
	v_pk_mul_f32 v[40:41], v[144:145], v[2:3]
	v_mov_b32_e32 v39, v75
	v_add_f32_e32 v36, v36, v40
	v_add_f32_e32 v40, v36, v41
	v_cmp_ngt_f32_e32 vcc, v40, v76
	s_and_saveexec_b64 s[42:43], vcc
	s_cbranch_execz .LBB0_418
	v_cmp_ngt_f32_e32 vcc, v40, v77
	v_mov_b32_e32 v36, v75
	s_and_saveexec_b64 s[44:45], vcc
	s_cbranch_execz .LBB0_417
	v_cmp_gt_f32_e32 vcc, v40, v38
	s_and_saveexec_b64 s[46:47], vcc
	s_cbranch_execz .LBB0_416
	v_mov_b32_e32 v38, v40
	v_mov_b32_e32 v37, v75
	s_branch .LBB0_416
